# flat barrier with 3 staggered outstanding polls of the go word
# baseline (speedup 1.0000x reference)
; __device__ __forceinline__ unsigned xb_ld(unsigned* p)              { return __hip_atomic_load(p, __ATOMIC_RELAXED, __HIP_MEMORY_SCOPE_AGENT); }
; __device__ __forceinline__ unsigned xb_add(unsigned* p, unsigned v) { return __hip_atomic_fetch_add(p, v, __ATOMIC_RELAXED, __HIP_MEMORY_SCOPE_AGENT); }
; #define XB_SPIN(cond, bar) do { unsigned _sp = 0; while (cond) { __builtin_amdgcn_s_sleep(1); \
;     if ((++_sp & 255u) == 0u) { if (xb_ld(&(bar)[XB_TMO])) break; if (_sp > XB_SPIN_CAP) { atomicAdd(&(bar)[XB_TMO], 1u); break; } } } } while (0)
; __device__ __forceinline__ void xcd_barrier(const XcdBarrier& b) {
;     ...
;             else XB_SPIN(xb_ld(&bar[XB_TOPGEN]) == tg, bar);
;             __builtin_amdgcn_fence(__ATOMIC_ACQUIRE, "agent");
;             xb_add(&bar[XB_XGEN(b.x)], 1u);
;             asm volatile("s_waitcnt vmcnt(0)" ::: "memory");
;         } else {
;             XB_SPIN(xb_ld(&bar[XB_XGEN(b.x)]) == gen, bar);
;             __builtin_amdgcn_fence(__ATOMIC_ACQUIRE, "agent");
;             asm volatile("s_waitcnt vmcnt(0)" ::: "memory");
.Lgb0_poll:
	global_load_dword v4, v1, s[6:7] offset:1024 sc1
	s_sleep 6
	global_load_dword v6, v1, s[6:7] offset:1024 sc1
	s_sleep 6
	global_load_dword v7, v1, s[6:7] offset:1024 sc1
.Lgb0_loop:
	s_waitcnt vmcnt(2)
	v_cmp_eq_u32_e32 vcc, 8, v4
	s_cbranch_vccnz .Lgb0_done
	global_load_dword v4, v1, s[6:7] offset:1024 sc1
	s_waitcnt vmcnt(2)
	v_cmp_eq_u32_e32 vcc, 8, v6
	s_cbranch_vccnz .Lgb0_done
	global_load_dword v6, v1, s[6:7] offset:1024 sc1
	s_waitcnt vmcnt(2)
	v_cmp_eq_u32_e32 vcc, 8, v7
	s_cbranch_vccnz .Lgb0_done
	global_load_dword v7, v1, s[6:7] offset:1024 sc1
	s_add_i32 s12, s12, 1
	s_cmp_lt_u32 s12, 0x8000
	s_cbranch_scc1 .Lgb0_loop

; __device__ __forceinline__ unsigned xb_ld(unsigned* p)              { return __hip_atomic_load(p, __ATOMIC_RELAXED, __HIP_MEMORY_SCOPE_AGENT); }
; __device__ __forceinline__ unsigned xb_add(unsigned* p, unsigned v) { return __hip_atomic_fetch_add(p, v, __ATOMIC_RELAXED, __HIP_MEMORY_SCOPE_AGENT); }
; #define XB_SPIN(cond, bar) do { unsigned _sp = 0; while (cond) { __builtin_amdgcn_s_sleep(1); \
;     if ((++_sp & 255u) == 0u) { if (xb_ld(&(bar)[XB_TMO])) break; if (_sp > XB_SPIN_CAP) { atomicAdd(&(bar)[XB_TMO], 1u); break; } } } } while (0)
; __device__ __forceinline__ void xcd_barrier(const XcdBarrier& b) {
;     ...
;             else XB_SPIN(xb_ld(&bar[XB_TOPGEN]) == tg, bar);
;             __builtin_amdgcn_fence(__ATOMIC_ACQUIRE, "agent");
;             xb_add(&bar[XB_XGEN(b.x)], 1u);
;             asm volatile("s_waitcnt vmcnt(0)" ::: "memory");
;         } else {
;             XB_SPIN(xb_ld(&bar[XB_XGEN(b.x)]) == gen, bar);
;             __builtin_amdgcn_fence(__ATOMIC_ACQUIRE, "agent");
;             asm volatile("s_waitcnt vmcnt(0)" ::: "memory");
.Lgb1_loop:
	s_waitcnt vmcnt(2)
	v_cmp_eq_u32_e32 vcc, 8, v4
	s_cbranch_vccnz .Lgb1_done
	global_load_dword v4, v1, s[6:7] offset:1024 sc1
	s_waitcnt vmcnt(2)
	v_cmp_eq_u32_e32 vcc, 8, v6
	s_cbranch_vccnz .Lgb1_done
	global_load_dword v6, v1, s[6:7] offset:1024 sc1
	s_waitcnt vmcnt(2)
	v_cmp_eq_u32_e32 vcc, 8, v7
	s_cbranch_vccnz .Lgb1_done
	global_load_dword v7, v1, s[6:7] offset:1024 sc1
	s_add_i32 s10, s10, 1
	s_cmp_lt_u32 s10, 0x8000
	s_cbranch_scc1 .Lgb1_loop

; __device__ __forceinline__ unsigned xb_ld(unsigned* p)              { return __hip_atomic_load(p, __ATOMIC_RELAXED, __HIP_MEMORY_SCOPE_AGENT); }
; __device__ __forceinline__ unsigned xb_add(unsigned* p, unsigned v) { return __hip_atomic_fetch_add(p, v, __ATOMIC_RELAXED, __HIP_MEMORY_SCOPE_AGENT); }
; #define XB_SPIN(cond, bar) do { unsigned _sp = 0; while (cond) { __builtin_amdgcn_s_sleep(1); \
;     if ((++_sp & 255u) == 0u) { if (xb_ld(&(bar)[XB_TMO])) break; if (_sp > XB_SPIN_CAP) { atomicAdd(&(bar)[XB_TMO], 1u); break; } } } } while (0)
; __device__ __forceinline__ void xcd_barrier(const XcdBarrier& b) {
;     ...
;             else XB_SPIN(xb_ld(&bar[XB_TOPGEN]) == tg, bar);
;             __builtin_amdgcn_fence(__ATOMIC_ACQUIRE, "agent");
;             xb_add(&bar[XB_XGEN(b.x)], 1u);
;             asm volatile("s_waitcnt vmcnt(0)" ::: "memory");
;         } else {
;             XB_SPIN(xb_ld(&bar[XB_XGEN(b.x)]) == gen, bar);
;             __builtin_amdgcn_fence(__ATOMIC_ACQUIRE, "agent");
;             asm volatile("s_waitcnt vmcnt(0)" ::: "memory");
.Lgb2_loop:
	s_waitcnt vmcnt(2)
	v_cmp_eq_u32_e32 vcc, 8, v4
	s_cbranch_vccnz .Lgb2_done
	global_load_dword v4, v1, s[6:7] offset:1024 sc1
	s_waitcnt vmcnt(2)
	v_cmp_eq_u32_e32 vcc, 8, v6
	s_cbranch_vccnz .Lgb2_done
	global_load_dword v6, v1, s[6:7] offset:1024 sc1
	s_waitcnt vmcnt(2)
	v_cmp_eq_u32_e32 vcc, 8, v7
	s_cbranch_vccnz .Lgb2_done
	global_load_dword v7, v1, s[6:7] offset:1024 sc1
	s_add_i32 s11, s11, 1
	s_cmp_lt_u32 s11, 0x8000
	s_cbranch_scc1 .Lgb2_loop

; __device__ __forceinline__ unsigned xb_ld(unsigned* p)              { return __hip_atomic_load(p, __ATOMIC_RELAXED, __HIP_MEMORY_SCOPE_AGENT); }
; __device__ __forceinline__ unsigned xb_add(unsigned* p, unsigned v) { return __hip_atomic_fetch_add(p, v, __ATOMIC_RELAXED, __HIP_MEMORY_SCOPE_AGENT); }
; #define XB_SPIN(cond, bar) do { unsigned _sp = 0; while (cond) { __builtin_amdgcn_s_sleep(1); \
;     if ((++_sp & 255u) == 0u) { if (xb_ld(&(bar)[XB_TMO])) break; if (_sp > XB_SPIN_CAP) { atomicAdd(&(bar)[XB_TMO], 1u); break; } } } } while (0)
; __device__ __forceinline__ void xcd_barrier(const XcdBarrier& b) {
;     ...
;             else XB_SPIN(xb_ld(&bar[XB_TOPGEN]) == tg, bar);
;             __builtin_amdgcn_fence(__ATOMIC_ACQUIRE, "agent");
;             xb_add(&bar[XB_XGEN(b.x)], 1u);
;             asm volatile("s_waitcnt vmcnt(0)" ::: "memory");
;         } else {
;             XB_SPIN(xb_ld(&bar[XB_XGEN(b.x)]) == gen, bar);
;             __builtin_amdgcn_fence(__ATOMIC_ACQUIRE, "agent");
;             asm volatile("s_waitcnt vmcnt(0)" ::: "memory");
.Lgb3_poll:
	global_load_dword v4, v1, s[8:9] offset:1024 sc1
	s_sleep 6
	global_load_dword v6, v1, s[8:9] offset:1024 sc1
	s_sleep 6
	global_load_dword v7, v1, s[8:9] offset:1024 sc1
.Lgb3_loop:
	s_waitcnt vmcnt(2)
	v_cmp_eq_u32_e32 vcc, 8, v4
	s_cbranch_vccnz .Lgb3_done
	global_load_dword v4, v1, s[8:9] offset:1024 sc1
	s_waitcnt vmcnt(2)
	v_cmp_eq_u32_e32 vcc, 8, v6
	s_cbranch_vccnz .Lgb3_done
	global_load_dword v6, v1, s[8:9] offset:1024 sc1
	s_waitcnt vmcnt(2)
	v_cmp_eq_u32_e32 vcc, 8, v7
	s_cbranch_vccnz .Lgb3_done
	global_load_dword v7, v1, s[8:9] offset:1024 sc1
	s_add_i32 s13, s13, 1
	s_cmp_lt_u32 s13, 0x8000
	s_cbranch_scc1 .Lgb3_loop

; __device__ __forceinline__ unsigned xb_ld(unsigned* p)              { return __hip_atomic_load(p, __ATOMIC_RELAXED, __HIP_MEMORY_SCOPE_AGENT); }
; __device__ __forceinline__ unsigned xb_add(unsigned* p, unsigned v) { return __hip_atomic_fetch_add(p, v, __ATOMIC_RELAXED, __HIP_MEMORY_SCOPE_AGENT); }
; #define XB_SPIN(cond, bar) do { unsigned _sp = 0; while (cond) { __builtin_amdgcn_s_sleep(1); \
;     if ((++_sp & 255u) == 0u) { if (xb_ld(&(bar)[XB_TMO])) break; if (_sp > XB_SPIN_CAP) { atomicAdd(&(bar)[XB_TMO], 1u); break; } } } } while (0)
; __device__ __forceinline__ void xcd_barrier(const XcdBarrier& b) {
;     ...
;             else XB_SPIN(xb_ld(&bar[XB_TOPGEN]) == tg, bar);
;             __builtin_amdgcn_fence(__ATOMIC_ACQUIRE, "agent");
;             xb_add(&bar[XB_XGEN(b.x)], 1u);
;             asm volatile("s_waitcnt vmcnt(0)" ::: "memory");
;         } else {
;             XB_SPIN(xb_ld(&bar[XB_XGEN(b.x)]) == gen, bar);
;             __builtin_amdgcn_fence(__ATOMIC_ACQUIRE, "agent");
;             asm volatile("s_waitcnt vmcnt(0)" ::: "memory");
.Lgb4_poll:
	global_load_dword v36, v1, s[8:9] offset:1024 sc1
	s_sleep 6
	global_load_dword v38, v1, s[8:9] offset:1024 sc1
	s_sleep 6
	global_load_dword v39, v1, s[8:9] offset:1024 sc1
.Lgb4_loop:
	s_waitcnt vmcnt(2)
	v_cmp_eq_u32_e32 vcc, 8, v36
	s_cbranch_vccnz .Lgb4_done
	global_load_dword v36, v1, s[8:9] offset:1024 sc1
	s_waitcnt vmcnt(2)
	v_cmp_eq_u32_e32 vcc, 8, v38
	s_cbranch_vccnz .Lgb4_done
	global_load_dword v38, v1, s[8:9] offset:1024 sc1
	s_waitcnt vmcnt(2)
	v_cmp_eq_u32_e32 vcc, 8, v39
	s_cbranch_vccnz .Lgb4_done
	global_load_dword v39, v1, s[8:9] offset:1024 sc1
	s_add_i32 s13, s13, 1
	s_cmp_lt_u32 s13, 0x8000
	s_cbranch_scc1 .Lgb4_loop

; __device__ __forceinline__ unsigned xb_ld(unsigned* p)              { return __hip_atomic_load(p, __ATOMIC_RELAXED, __HIP_MEMORY_SCOPE_AGENT); }
; __device__ __forceinline__ unsigned xb_add(unsigned* p, unsigned v) { return __hip_atomic_fetch_add(p, v, __ATOMIC_RELAXED, __HIP_MEMORY_SCOPE_AGENT); }
; #define XB_SPIN(cond, bar) do { unsigned _sp = 0; while (cond) { __builtin_amdgcn_s_sleep(1); \
;     if ((++_sp & 255u) == 0u) { if (xb_ld(&(bar)[XB_TMO])) break; if (_sp > XB_SPIN_CAP) { atomicAdd(&(bar)[XB_TMO], 1u); break; } } } } while (0)
; __device__ __forceinline__ void xcd_barrier(const XcdBarrier& b) {
;     ...
;             else XB_SPIN(xb_ld(&bar[XB_TOPGEN]) == tg, bar);
;             __builtin_amdgcn_fence(__ATOMIC_ACQUIRE, "agent");
;             xb_add(&bar[XB_XGEN(b.x)], 1u);
;             asm volatile("s_waitcnt vmcnt(0)" ::: "memory");
;         } else {
;             XB_SPIN(xb_ld(&bar[XB_XGEN(b.x)]) == gen, bar);
;             __builtin_amdgcn_fence(__ATOMIC_ACQUIRE, "agent");
;             asm volatile("s_waitcnt vmcnt(0)" ::: "memory");
.Lgb5_loop:
	s_waitcnt vmcnt(2)
	v_cmp_eq_u32_e32 vcc, 8, v4
	s_cbranch_vccnz .Lgb5_done
	global_load_dword v4, v1, s[6:7] offset:1024 sc1
	s_waitcnt vmcnt(2)
	v_cmp_eq_u32_e32 vcc, 8, v6
	s_cbranch_vccnz .Lgb5_done
	global_load_dword v6, v1, s[6:7] offset:1024 sc1
	s_waitcnt vmcnt(2)
	v_cmp_eq_u32_e32 vcc, 8, v7
	s_cbranch_vccnz .Lgb5_done
	global_load_dword v7, v1, s[6:7] offset:1024 sc1
	s_add_i32 s13, s13, 1
	s_cmp_lt_u32 s13, 0x8000
	s_cbranch_scc1 .Lgb5_loop

; __device__ __forceinline__ unsigned xb_ld(unsigned* p)              { return __hip_atomic_load(p, __ATOMIC_RELAXED, __HIP_MEMORY_SCOPE_AGENT); }
; __device__ __forceinline__ unsigned xb_add(unsigned* p, unsigned v) { return __hip_atomic_fetch_add(p, v, __ATOMIC_RELAXED, __HIP_MEMORY_SCOPE_AGENT); }
; #define XB_SPIN(cond, bar) do { unsigned _sp = 0; while (cond) { __builtin_amdgcn_s_sleep(1); \
;     if ((++_sp & 255u) == 0u) { if (xb_ld(&(bar)[XB_TMO])) break; if (_sp > XB_SPIN_CAP) { atomicAdd(&(bar)[XB_TMO], 1u); break; } } } } while (0)
; __device__ __forceinline__ void xcd_barrier(const XcdBarrier& b) {
;     ...
;             else XB_SPIN(xb_ld(&bar[XB_TOPGEN]) == tg, bar);
;             __builtin_amdgcn_fence(__ATOMIC_ACQUIRE, "agent");
;             xb_add(&bar[XB_XGEN(b.x)], 1u);
;             asm volatile("s_waitcnt vmcnt(0)" ::: "memory");
;         } else {
;             XB_SPIN(xb_ld(&bar[XB_XGEN(b.x)]) == gen, bar);
;             __builtin_amdgcn_fence(__ATOMIC_ACQUIRE, "agent");
;             asm volatile("s_waitcnt vmcnt(0)" ::: "memory");
.Lgb8_poll:
	global_load_dword v3, v0, s[4:5] offset:1024 sc1
	s_sleep 6
	global_load_dword v5, v0, s[4:5] offset:1024 sc1
	s_sleep 6
	global_load_dword v6, v0, s[4:5] offset:1024 sc1
.Lgb8_loop:
	s_waitcnt vmcnt(2)
	v_cmp_eq_u32_e32 vcc, 8, v3
	s_cbranch_vccnz .Lgb8_done
	global_load_dword v3, v0, s[4:5] offset:1024 sc1
	s_waitcnt vmcnt(2)
	v_cmp_eq_u32_e32 vcc, 8, v5
	s_cbranch_vccnz .Lgb8_done
	global_load_dword v5, v0, s[4:5] offset:1024 sc1
	s_waitcnt vmcnt(2)
	v_cmp_eq_u32_e32 vcc, 8, v6
	s_cbranch_vccnz .Lgb8_done
	global_load_dword v6, v0, s[4:5] offset:1024 sc1
	s_add_i32 s9, s9, 1
	s_cmp_lt_u32 s9, 0x8000
	s_cbranch_scc1 .Lgb8_loop
